# lru_s3: chunk carry (CR) loads issued at item top instead of right after the barrier
# speedup vs baseline: 1.0047x; 1.0047x over previous
; #define LAS __attribute__((address_space(3)))
; __device__ __forceinline__ float bf2f(bf16_t b) { return __uint_as_float(((unsigned)b) << 16); }
; __device__ __forceinline__ int opaque_tid() { int t = threadIdx.x; asm volatile("" : "+v"(t)); return t; }
; #define p (*kparams())
; __device__ __forceinline__ void lru_s3_item(CParams& p, int item, LAS unsigned char* lds) {
;     const int cidx = item >> 3, kb = item & 7, b = cidx / NCHK, c = cidx % NCHK;
;     const int tid = opaque_tid(), j = tid & 63, tq = tid >> 6, ch = kb * 64 + j;
;     LAS float* AG = (LAS float*)lds;
;     const bf16_t* P = (const bf16_t*)(p.ws + R_PMIX); const bf16_t* LA = (const bf16_t*)(p.ws + R_LA); const bf16_t* BB = (const bf16_t*)(p.ws + R_BB);
;     bf16_t* Z = (bf16_t*)(p.ws + OFF_Z);
;     float av[2][16], bv[2][16];
;     size_t ro[16];
; #pragma unroll
;     for (int tt = 0; tt < 16; ++tt) ro[tt] = (size_t)row_bci(b, c, 16 * tq + tt);
; #pragma unroll
;     for (int dir = 0; dir < 2; ++dir)
; #pragma unroll
;         for (int tt = 0; tt < 16; ++tt) { const size_t o = (size_t)dir * MP * W + ro[tt] * W + ch; av[dir][tt] = bf2f(LA[o]); bv[dir][tt] = bf2f(BB[o]); }
.LBB0_755:
	s_mov_b64 s[4:5], s[0:1]
	s_ashr_i32 s28, s11, 3
	s_load_dwordx2 s[4:5], s[4:5], 0xe8
	s_mul_hi_i32 s10, s28, 0x7e07e07f
	s_lshr_b32 s14, s10, 31
	s_ashr_i32 s10, s10, 5
	s_add_i32 s14, s10, s14
	s_mul_i32 s36, s14, 0x41
	s_sub_i32 s39, s28, s36
	v_mov_b32_e32 v0, v206
	s_and_b32 s10, s9, 0x1c0
	s_waitcnt lgkmcnt(0)
	s_add_u32 s30, s4, 0x2db02000
	v_and_b32_e32 v93, 63, v0
	v_or_b32_e32 v82, s10, v93
	s_addc_u32 s31, s5, 0
	s_lshl_b32 s15, s14, 13
	s_lshl_b32 s10, s39, 7
	s_add_i32 s15, s15, s10
	s_lshl_b32 s14, s14, 7
	s_addk_i32 s15, 0xff80
	s_addk_i32 s14, 0x4000
	v_ashrrev_i32_e32 v85, 6, v0
	s_cmp_eq_u32 s39, 0
	v_lshlrev_b32_e32 v84, 4, v85
	s_cselect_b32 s14, s14, s15
	v_add_u32_e32 v32, s14, v84
	v_ashrrev_i32_e32 v33, 31, v32
	v_lshlrev_b64 v[34:35], 9, v[32:33]
	s_add_u32 s40, s4, 0x2ba82000
	v_or_b32_e32 v36, v34, v82
	v_mov_b32_e32 v37, v35
	s_addc_u32 s41, s5, 0
	v_lshlrev_b64 v[36:37], 1, v[36:37]
	v_lshl_add_u64 v[38:39], s[40:41], 0, v[36:37]
	global_load_ushort v120, v[38:39], off
	v_lshl_add_u64 v[36:37], s[30:31], 0, v[36:37]
	v_or_b32_e32 v30, 1, v32
	v_ashrrev_i32_e32 v31, 31, v30
	v_or_b32_e32 v28, 2, v32
	v_ashrrev_i32_e32 v29, 31, v28
	v_or_b32_e32 v26, 3, v32
	v_ashrrev_i32_e32 v27, 31, v26
	v_or_b32_e32 v24, 4, v32
	v_ashrrev_i32_e32 v25, 31, v24
	v_or_b32_e32 v22, 5, v32
	v_ashrrev_i32_e32 v23, 31, v22
	v_or_b32_e32 v20, 6, v32
	v_ashrrev_i32_e32 v21, 31, v20
	v_or_b32_e32 v18, 7, v32
	v_ashrrev_i32_e32 v19, 31, v18
	v_or_b32_e32 v16, 8, v32
	v_ashrrev_i32_e32 v17, 31, v16
	v_or_b32_e32 v14, 9, v32
	v_ashrrev_i32_e32 v15, 31, v14
	v_or_b32_e32 v12, 10, v32
	v_ashrrev_i32_e32 v13, 31, v12
	v_or_b32_e32 v10, 11, v32
	v_ashrrev_i32_e32 v11, 31, v10
	v_or_b32_e32 v8, 12, v32
	v_ashrrev_i32_e32 v9, 31, v8
	v_or_b32_e32 v6, 13, v32
	v_ashrrev_i32_e32 v7, 31, v6
	v_or_b32_e32 v4, 14, v32
	v_ashrrev_i32_e32 v5, 31, v4
	v_or_b32_e32 v0, 15, v32
	v_ashrrev_i32_e32 v1, 31, v0
	global_load_ushort v121, v[36:37], off
	v_lshlrev_b64 v[36:37], 9, v[30:31]
	v_or_b32_e32 v38, v36, v82
	v_mov_b32_e32 v39, v37
	v_lshlrev_b64 v[38:39], 1, v[38:39]
	v_lshl_add_u64 v[40:41], s[40:41], 0, v[38:39]
	v_lshl_add_u64 v[38:39], s[30:31], 0, v[38:39]
	global_load_ushort v122, v[40:41], off
	global_load_ushort v123, v[38:39], off
	v_lshlrev_b64 v[38:39], 9, v[28:29]
	v_or_b32_e32 v40, v38, v82
	v_mov_b32_e32 v41, v39
	v_lshlrev_b64 v[40:41], 1, v[40:41]
	v_lshl_add_u64 v[42:43], s[40:41], 0, v[40:41]
	v_lshl_add_u64 v[40:41], s[30:31], 0, v[40:41]
	global_load_ushort v124, v[42:43], off
	global_load_ushort v125, v[40:41], off
	v_lshlrev_b64 v[40:41], 9, v[26:27]
	v_or_b32_e32 v42, v40, v82
	v_mov_b32_e32 v43, v41
	v_lshlrev_b64 v[42:43], 1, v[42:43]
	v_lshl_add_u64 v[44:45], s[40:41], 0, v[42:43]
	v_lshl_add_u64 v[42:43], s[30:31], 0, v[42:43]
	global_load_ushort v126, v[44:45], off
	global_load_ushort v127, v[42:43], off
	v_lshlrev_b64 v[42:43], 9, v[24:25]
	v_or_b32_e32 v44, v42, v82
	v_mov_b32_e32 v45, v43
	v_lshlrev_b64 v[44:45], 1, v[44:45]
	v_lshl_add_u64 v[46:47], s[40:41], 0, v[44:45]
	v_lshl_add_u64 v[44:45], s[30:31], 0, v[44:45]
	global_load_ushort v128, v[46:47], off
	global_load_ushort v129, v[44:45], off
	v_lshlrev_b64 v[44:45], 9, v[22:23]
	v_or_b32_e32 v46, v44, v82
	v_mov_b32_e32 v47, v45
	v_lshlrev_b64 v[46:47], 1, v[46:47]
	v_lshl_add_u64 v[48:49], s[40:41], 0, v[46:47]
	v_lshl_add_u64 v[46:47], s[30:31], 0, v[46:47]
	global_load_ushort v130, v[48:49], off
	global_load_ushort v131, v[46:47], off
	v_lshlrev_b64 v[46:47], 9, v[20:21]
	v_or_b32_e32 v48, v46, v82
	v_mov_b32_e32 v49, v47
	v_lshlrev_b64 v[48:49], 1, v[48:49]
	v_lshl_add_u64 v[50:51], s[40:41], 0, v[48:49]
	v_lshl_add_u64 v[48:49], s[30:31], 0, v[48:49]
	global_load_ushort v132, v[50:51], off
	global_load_ushort v133, v[48:49], off
	v_lshlrev_b64 v[48:49], 9, v[18:19]
	v_or_b32_e32 v50, v48, v82
	v_mov_b32_e32 v51, v49
	v_lshlrev_b64 v[50:51], 1, v[50:51]
	v_lshl_add_u64 v[52:53], s[40:41], 0, v[50:51]
	v_lshl_add_u64 v[50:51], s[30:31], 0, v[50:51]
	global_load_ushort v134, v[52:53], off
	global_load_ushort v135, v[50:51], off
	v_lshlrev_b64 v[50:51], 9, v[16:17]
	v_or_b32_e32 v52, v50, v82
	v_mov_b32_e32 v53, v51
	v_lshlrev_b64 v[52:53], 1, v[52:53]
	v_lshl_add_u64 v[54:55], s[40:41], 0, v[52:53]
	v_lshl_add_u64 v[52:53], s[30:31], 0, v[52:53]
	global_load_ushort v136, v[54:55], off
	global_load_ushort v137, v[52:53], off
	v_lshlrev_b64 v[52:53], 9, v[14:15]
	v_or_b32_e32 v54, v52, v82
	v_mov_b32_e32 v55, v53
	v_lshlrev_b64 v[54:55], 1, v[54:55]
	v_lshl_add_u64 v[56:57], s[40:41], 0, v[54:55]
	v_lshl_add_u64 v[54:55], s[30:31], 0, v[54:55]
	global_load_ushort v138, v[56:57], off
	global_load_ushort v139, v[54:55], off
	v_lshlrev_b64 v[54:55], 9, v[12:13]
	v_or_b32_e32 v56, v54, v82
	v_mov_b32_e32 v57, v55
	v_lshlrev_b64 v[56:57], 1, v[56:57]
	v_lshl_add_u64 v[58:59], s[40:41], 0, v[56:57]
	v_lshl_add_u64 v[56:57], s[30:31], 0, v[56:57]
	global_load_ushort v140, v[58:59], off
	global_load_ushort v141, v[56:57], off
	v_lshlrev_b64 v[56:57], 9, v[10:11]
	v_or_b32_e32 v58, v56, v82
	v_mov_b32_e32 v59, v57
	v_lshlrev_b64 v[58:59], 1, v[58:59]
	v_lshl_add_u64 v[60:61], s[40:41], 0, v[58:59]
	v_lshl_add_u64 v[58:59], s[30:31], 0, v[58:59]
	global_load_ushort v142, v[60:61], off
	global_load_ushort v143, v[58:59], off
	v_lshlrev_b64 v[58:59], 9, v[8:9]
	v_or_b32_e32 v60, v58, v82
	v_mov_b32_e32 v61, v59
	v_lshlrev_b64 v[60:61], 1, v[60:61]
	v_lshl_add_u64 v[62:63], s[40:41], 0, v[60:61]
	v_lshl_add_u64 v[60:61], s[30:31], 0, v[60:61]
	global_load_ushort v144, v[62:63], off
	global_load_ushort v145, v[60:61], off
	v_lshlrev_b64 v[60:61], 9, v[6:7]
; __device__ __forceinline__ float bf2f(bf16_t b) { return __uint_as_float(((unsigned)b) << 16); }
; #define p (*kparams())
; __device__ __forceinline__ void lru_s3_item(CParams& p, int item, LAS unsigned char* lds) {
;     ...
;     for (int tt = 0; tt < 16; ++tt) ro[tt] = (size_t)row_bci(b, c, 16 * tq + tt);
; #pragma unroll
;     for (int dir = 0; dir < 2; ++dir)
; #pragma unroll
;         for (int tt = 0; tt < 16; ++tt) { const size_t o = (size_t)dir * MP * W + ro[tt] * W + ch; av[dir][tt] = bf2f(LA[o]); bv[dir][tt] = bf2f(BB[o]); }
;     ...
;         float h = ((const float*)(p.ws + R_CR))[(size_t)((dir * 2 + b) * NCHK + c) * W + ch];
;         for (int s = 0; s < 7; ++s) { const int q = dir ? 7 - s : s; const bool use = dir ? (q > tq) : (q < tq);
;             const float a = AG[((q * 2 + dir) * 2 + 0) * 64 + j], bq = AG[((q * 2 + dir) * 2 + 1) * 64 + j]; if (use) h = a * h + bq; }
; #pragma unroll
;         for (int s = 0; s < 16; ++s) { const int tt = dir ? 15 - s : s; h = av[dir][tt] * h + bv[dir][tt]; if (dir == 0) hs[tt] = h; else hs[tt] += h; }
;     }
; #pragma unroll
;     for (int tt = 0; tt < 16; ++tt) { const int i = 16 * tq + tt; const bool valid = (c * 128 + i - 112) >= 0;
;         const float ga = bf2f(P[ro[tt] * NMIX + 512 + ch]);
	v_or_b32_e32 v62, v60, v82
	v_mov_b32_e32 v63, v61
	v_lshlrev_b64 v[62:63], 1, v[62:63]
	v_lshl_add_u64 v[64:65], s[40:41], 0, v[62:63]
	v_lshl_add_u64 v[62:63], s[30:31], 0, v[62:63]
	global_load_ushort v146, v[64:65], off
	global_load_ushort v147, v[62:63], off
	v_lshlrev_b64 v[62:63], 9, v[4:5]
	v_or_b32_e32 v64, v62, v82
	v_mov_b32_e32 v65, v63
	v_lshlrev_b64 v[64:65], 1, v[64:65]
	v_lshl_add_u64 v[66:67], s[40:41], 0, v[64:65]
	v_lshl_add_u64 v[64:65], s[30:31], 0, v[64:65]
	global_load_ushort v148, v[66:67], off
	global_load_ushort v149, v[64:65], off
	v_lshlrev_b64 v[64:65], 9, v[0:1]
	v_or_b32_e32 v66, v64, v82
	v_mov_b32_e32 v67, v65
	v_lshlrev_b64 v[66:67], 1, v[66:67]
	v_lshl_add_u64 v[86:87], s[40:41], 0, v[66:67]
	v_lshl_add_u64 v[66:67], s[30:31], 0, v[66:67]
	global_load_ushort v150, v[86:87], off
	global_load_ushort v151, v[66:67], off
	v_mov_b32_e32 v67, v2
	v_or_b32_e32 v66, 0x820000, v82
	v_lshl_add_u64 v[34:35], v[34:35], 0, v[66:67]
	v_lshlrev_b64 v[86:87], 1, v[34:35]
	v_lshl_add_u64 v[34:35], s[40:41], 0, v[86:87]
	v_lshl_add_u64 v[86:87], s[30:31], 0, v[86:87]
	global_load_ushort v152, v[34:35], off
	v_lshl_add_u64 v[36:37], v[36:37], 0, v[66:67]
	global_load_ushort v153, v[86:87], off
	v_lshlrev_b64 v[36:37], 1, v[36:37]
	v_lshl_add_u64 v[86:87], s[40:41], 0, v[36:37]
	v_lshl_add_u64 v[36:37], s[30:31], 0, v[36:37]
	global_load_ushort v154, v[36:37], off
	global_load_ushort v155, v[86:87], off
	v_lshl_add_u64 v[36:37], v[38:39], 0, v[66:67]
	v_lshlrev_b64 v[38:39], 1, v[36:37]
	v_lshl_add_u64 v[36:37], s[40:41], 0, v[38:39]
	v_lshl_add_u64 v[38:39], s[30:31], 0, v[38:39]
	global_load_ushort v156, v[36:37], off
	global_load_ushort v157, v[38:39], off
	v_lshl_add_u64 v[38:39], v[40:41], 0, v[66:67]
	v_lshlrev_b64 v[38:39], 1, v[38:39]
	v_lshl_add_u64 v[40:41], s[40:41], 0, v[38:39]
	v_lshl_add_u64 v[38:39], s[30:31], 0, v[38:39]
	global_load_ushort v158, v[38:39], off
	global_load_ushort v159, v[40:41], off
	v_lshl_add_u64 v[38:39], v[42:43], 0, v[66:67]
	v_lshlrev_b64 v[38:39], 1, v[38:39]
	v_lshl_add_u64 v[40:41], s[40:41], 0, v[38:39]
	v_lshl_add_u64 v[38:39], s[30:31], 0, v[38:39]
	global_load_ushort v160, v[40:41], off
	global_load_ushort v161, v[38:39], off
	v_lshl_add_u64 v[38:39], v[44:45], 0, v[66:67]
	v_lshlrev_b64 v[38:39], 1, v[38:39]
	v_lshl_add_u64 v[40:41], s[40:41], 0, v[38:39]
	v_lshl_add_u64 v[38:39], s[30:31], 0, v[38:39]
	global_load_ushort v162, v[40:41], off
	s_nop 0
	global_load_ushort v163, v[38:39], off
	v_lshl_add_u64 v[38:39], v[46:47], 0, v[66:67]
	v_lshlrev_b64 v[38:39], 1, v[38:39]
	v_lshl_add_u64 v[40:41], s[40:41], 0, v[38:39]
	v_lshl_add_u64 v[38:39], s[30:31], 0, v[38:39]
	global_load_ushort v164, v[40:41], off
	global_load_ushort v165, v[38:39], off
	v_lshl_add_u64 v[38:39], v[48:49], 0, v[66:67]
	v_lshlrev_b64 v[38:39], 1, v[38:39]
	v_lshl_add_u64 v[40:41], s[40:41], 0, v[38:39]
	v_lshl_add_u64 v[38:39], s[30:31], 0, v[38:39]
	global_load_ushort v172, v[40:41], off
	s_nop 0
	global_load_ushort v173, v[38:39], off
	v_lshl_add_u64 v[38:39], v[50:51], 0, v[66:67]
	v_lshlrev_b64 v[38:39], 1, v[38:39]
	v_lshl_add_u64 v[40:41], s[40:41], 0, v[38:39]
	v_lshl_add_u64 v[38:39], s[30:31], 0, v[38:39]
	global_load_ushort v174, v[40:41], off
	s_nop 0
	global_load_ushort v175, v[38:39], off
	v_lshl_add_u64 v[38:39], v[52:53], 0, v[66:67]
	v_lshlrev_b64 v[38:39], 1, v[38:39]
	v_lshl_add_u64 v[40:41], s[40:41], 0, v[38:39]
	v_lshl_add_u64 v[38:39], s[30:31], 0, v[38:39]
	global_load_ushort v176, v[40:41], off
	s_nop 0
	global_load_ushort v177, v[38:39], off
	v_lshl_add_u64 v[38:39], v[54:55], 0, v[66:67]
	v_lshlrev_b64 v[38:39], 1, v[38:39]
	v_lshl_add_u64 v[40:41], s[40:41], 0, v[38:39]
	v_lshl_add_u64 v[38:39], s[30:31], 0, v[38:39]
	global_load_ushort v178, v[40:41], off
	s_nop 0
	global_load_ushort v179, v[38:39], off
	v_lshl_add_u64 v[38:39], v[56:57], 0, v[66:67]
	v_lshlrev_b64 v[38:39], 1, v[38:39]
	v_lshl_add_u64 v[40:41], s[40:41], 0, v[38:39]
	v_lshl_add_u64 v[38:39], s[30:31], 0, v[38:39]
	global_load_ushort v180, v[40:41], off
	global_load_ushort v181, v[38:39], off
	v_lshl_add_u64 v[38:39], v[58:59], 0, v[66:67]
	v_lshlrev_b64 v[38:39], 1, v[38:39]
	v_lshl_add_u64 v[40:41], s[40:41], 0, v[38:39]
	v_lshl_add_u64 v[38:39], s[30:31], 0, v[38:39]
	global_load_ushort v182, v[40:41], off
	s_nop 0
	global_load_ushort v183, v[38:39], off
	v_lshl_add_u64 v[38:39], v[60:61], 0, v[66:67]
	v_lshlrev_b64 v[38:39], 1, v[38:39]
	v_lshl_add_u64 v[48:49], s[40:41], 0, v[38:39]
	v_lshl_add_u64 v[38:39], s[30:31], 0, v[38:39]
	global_load_ushort v184, v[48:49], off
	s_nop 0
	global_load_ushort v185, v[38:39], off
	v_lshl_add_u64 v[48:49], v[62:63], 0, v[66:67]
	v_lshlrev_b64 v[48:49], 1, v[48:49]
	v_lshl_add_u64 v[50:51], s[40:41], 0, v[48:49]
	v_lshl_add_u64 v[48:49], s[30:31], 0, v[48:49]
	global_load_ushort v186, v[50:51], off
	global_load_ushort v187, v[48:49], off
	v_lshl_add_u64 v[48:49], v[64:65], 0, v[66:67]
	v_lshlrev_b64 v[48:49], 1, v[48:49]
	v_lshl_add_u64 v[50:51], s[40:41], 0, v[48:49]
	global_load_ushort v188, v[50:51], off
	v_lshl_add_u64 v[48:49], s[30:31], 0, v[48:49]
	global_load_ushort v189, v[48:49], off
	v_lshlrev_b32_e32 v222, 1, v82
	v_add_u32_e32 v222, 0x19602400, v222
	v_mov_b32_e32 v223, 0x3800
	v_mad_u32_u24 v224, v32, v223, v222
	global_load_ushort v190, v224, s[4:5]
	v_mad_u32_u24 v225, v30, v223, v222
	global_load_ushort v191, v225, s[4:5]
	v_mad_u32_u24 v224, v28, v223, v222
	global_load_ushort v192, v224, s[4:5]
	v_mad_u32_u24 v225, v26, v223, v222
	global_load_ushort v193, v225, s[4:5]
	v_mad_u32_u24 v224, v24, v223, v222
	global_load_ushort v194, v224, s[4:5]
	v_mad_u32_u24 v225, v22, v223, v222
	global_load_ushort v195, v225, s[4:5]
	v_mad_u32_u24 v224, v20, v223, v222
	global_load_ushort v196, v224, s[4:5]
	v_mad_u32_u24 v225, v18, v223, v222
	global_load_ushort v197, v225, s[4:5]
	v_mad_u32_u24 v224, v16, v223, v222
	global_load_ushort v198, v224, s[4:5]
	v_mad_u32_u24 v225, v14, v223, v222
	global_load_ushort v199, v225, s[4:5]
	v_mad_u32_u24 v224, v12, v223, v222
	global_load_ushort v200, v224, s[4:5]
	v_mad_u32_u24 v225, v10, v223, v222
	global_load_ushort v201, v225, s[4:5]
	v_mad_u32_u24 v224, v8, v223, v222
	global_load_ushort v202, v224, s[4:5]
	v_mad_u32_u24 v225, v6, v223, v222
	global_load_ushort v203, v225, s[4:5]
	v_mad_u32_u24 v224, v4, v223, v222
	global_load_ushort v204, v224, s[4:5]
	v_mad_u32_u24 v225, v0, v223, v222
	global_load_ushort v205, v225, s[4:5]
	v_lshlrev_b32_e32 v226, 2, v82
	v_mov_b32_e32 v227, s28
	v_lshl_add_u32 v226, v227, 11, v226
	v_add_u32_e32 v226, 0x3a1ee000, v226
	global_load_dword v228, v226, s[4:5]
	v_add_u32_e32 v227, 0x41000, v226
	global_load_dword v229, v227, s[4:5]
	s_waitcnt vmcnt(0)
; #define p (*kparams())
; __device__ __forceinline__ void lru_s3_item(CParams& p, int item, LAS unsigned char* lds) {
;     ...
;     __syncthreads();
; #pragma unroll
;     for (int dir = 0; dir < 2; ++dir) { float Aq = 1.f, Bq = 0.f;
; #pragma unroll
;         for (int s = 0; s < 16; ++s) { const int tt = dir ? 15 - s : s; const float a = __expf(av[dir][tt]); av[dir][tt] = a; Bq = a * Bq + bv[dir][tt]; Aq *= a; }
;         AG[((tq * 2 + dir) * 2 + 0) * 64 + j] = Aq; AG[((tq * 2 + dir) * 2 + 1) * 64 + j] = Bq; }
;     __syncthreads();
;     float hs[16];
; #pragma unroll
;     for (int dir = 0; dir < 2; ++dir) {
;         float h = ((const float*)(p.ws + R_CR))[(size_t)((dir * 2 + b) * NCHK + c) * W + ch];
;         for (int s = 0; s < 7; ++s) { const int q = dir ? 7 - s : s; const bool use = dir ? (q > tq) : (q < tq);
;             const float a = AG[((q * 2 + dir) * 2 + 0) * 64 + j], bq = AG[((q * 2 + dir) * 2 + 1) * 64 + j]; if (use) h = a * h + bq; }
	s_mov_b64 s[14:15], 0x3a1ee000
	s_ashr_i32 s29, s28, 31
	v_cmp_lt_i32_e32 vcc, 0, v85
	v_lshlrev_b32_e32 v94, 16, v120
	v_lshlrev_b32_e32 v83, 16, v121
	v_lshlrev_b32_e32 v95, 16, v122
	v_lshlrev_b32_e32 v81, 16, v123
	v_lshlrev_b32_e32 v96, 16, v124
	v_lshlrev_b32_e32 v80, 16, v125
	v_lshlrev_b32_e32 v97, 16, v126
	v_lshlrev_b32_e32 v79, 16, v127
	v_lshlrev_b32_e32 v98, 16, v128
	v_lshlrev_b32_e32 v78, 16, v129
	v_lshlrev_b32_e32 v99, 16, v130
	v_lshlrev_b32_e32 v77, 16, v131
	v_lshlrev_b32_e32 v100, 16, v132
	v_lshlrev_b32_e32 v76, 16, v133
	v_lshlrev_b32_e32 v101, 16, v134
	v_lshlrev_b32_e32 v75, 16, v135
	v_lshlrev_b32_e32 v102, 16, v136
	v_lshlrev_b32_e32 v74, 16, v137
	v_lshlrev_b32_e32 v103, 16, v138
	v_lshlrev_b32_e32 v73, 16, v139
	v_lshlrev_b32_e32 v104, 16, v140
	v_lshlrev_b32_e32 v72, 16, v141
	v_lshlrev_b32_e32 v105, 16, v142
	v_lshlrev_b32_e32 v71, 16, v143
	v_lshlrev_b32_e32 v107, 16, v144
	v_lshlrev_b32_e32 v70, 16, v145
	v_lshlrev_b32_e32 v108, 16, v146
	v_lshlrev_b32_e32 v69, 16, v147
	v_lshlrev_b32_e32 v109, 16, v148
	v_lshlrev_b32_e32 v3, 16, v149
	v_lshlrev_b32_e32 v111, 16, v150
	v_lshlrev_b32_e32 v68, 16, v151
	v_lshlrev_b32_e32 v34, 16, v152
	v_mul_f32_e32 v34, 0x3fb8aa3b, v34
	v_lshlrev_b32_e32 v92, 16, v153
	v_lshlrev_b32_e32 v91, 16, v154
	v_lshlrev_b32_e32 v35, 16, v155
	v_mul_f32_e32 v35, 0x3fb8aa3b, v35
	v_lshlrev_b32_e32 v36, 16, v156
	v_mul_f32_e32 v36, 0x3fb8aa3b, v36
	v_exp_f32_e32 v36, v36
	v_lshlrev_b32_e32 v90, 16, v157
	v_lshlrev_b32_e32 v89, 16, v158
	v_lshlrev_b32_e32 v37, 16, v159
	v_mul_f32_e32 v37, 0x3fb8aa3b, v37
	v_exp_f32_e32 v37, v37
	v_lshlrev_b32_e32 v106, 16, v160
	v_lshlrev_b32_e32 v88, 16, v161
	v_lshlrev_b32_e32 v110, 16, v162
	v_lshlrev_b32_e32 v87, 16, v163
	v_mul_f32_e32 v46, 0x3fb8aa3b, v94
	v_lshlrev_b32_e32 v112, 16, v164
	v_lshlrev_b32_e32 v86, 16, v165
	v_lshlrev_b32_e32 v113, 16, v172
	v_lshlrev_b32_e32 v47, 16, v173
	v_lshlrev_b32_e32 v114, 16, v174
	v_lshlrev_b32_e32 v45, 16, v175
	v_lshlrev_b32_e32 v115, 16, v176
	v_lshlrev_b32_e32 v44, 16, v177
	v_lshlrev_b32_e32 v55, 16, v178
	v_mul_f32_e32 v55, 0x3fb8aa3b, v55
	v_lshlrev_b32_e32 v43, 16, v179
	v_exp_f32_e32 v55, v55
	v_lshlrev_b32_e32 v116, 16, v180
	v_lshlrev_b32_e32 v42, 16, v181
	v_lshlrev_b32_e32 v117, 16, v182
	v_lshlrev_b32_e32 v40, 16, v183
	v_lshl_add_u32 v63, v93, 2, 0
	v_lshlrev_b32_e32 v118, 16, v184
	v_lshlrev_b32_e32 v39, 16, v185
	v_lshlrev_b32_e32 v119, 16, v186
	v_exp_f32_e32 v64, v46
	v_lshl_add_u32 v66, v85, 10, v63
	v_fma_f32 v46, 0, v64, v83
	v_lshlrev_b32_e32 v38, 16, v187
	v_lshlrev_b32_e32 v65, 16, v188
	v_mul_f32_e32 v48, 0x3fb8aa3b, v95
	v_exp_f32_e32 v62, v48
	v_mul_f32_e32 v49, 0x3fb8aa3b, v96
	v_exp_f32_e32 v61, v49
	v_mul_f32_e32 v49, 0x3fb8aa3b, v97
	v_exp_f32_e32 v60, v49
	v_mul_f32_e32 v49, 0x3fb8aa3b, v98
	v_exp_f32_e32 v59, v49
	v_mul_f32_e32 v49, 0x3fb8aa3b, v99
	v_mul_f32_e32 v48, v64, v62
	v_exp_f32_e32 v58, v49
	v_mul_f32_e32 v49, 0x3fb8aa3b, v100
	v_mul_f32_e32 v48, v48, v61
	v_exp_f32_e32 v57, v49
	v_mul_f32_e32 v49, 0x3fb8aa3b, v101
	v_mul_f32_e32 v48, v48, v60
	v_exp_f32_e32 v56, v49
	v_mul_f32_e32 v49, 0x3fb8aa3b, v102
	v_mul_f32_e32 v48, v48, v59
	v_exp_f32_e32 v54, v49
	v_mul_f32_e32 v49, 0x3fb8aa3b, v103
	v_fma_f32 v46, v46, v62, v81
	v_mul_f32_e32 v48, v48, v58
	v_exp_f32_e32 v53, v49
	v_mul_f32_e32 v49, 0x3fb8aa3b, v104
	v_fma_f32 v46, v46, v61, v80
	v_mul_f32_e32 v48, v48, v57
	v_exp_f32_e32 v52, v49
	v_mul_f32_e32 v49, 0x3fb8aa3b, v105
	v_fma_f32 v46, v46, v60, v79
	v_mul_f32_e32 v48, v48, v56
	v_exp_f32_e32 v51, v49
	v_mul_f32_e32 v49, 0x3fb8aa3b, v107
	v_fma_f32 v46, v46, v59, v78
	v_mul_f32_e32 v48, v48, v54
	v_exp_f32_e32 v50, v49
	v_mul_f32_e32 v49, 0x3fb8aa3b, v108
	v_fma_f32 v46, v46, v58, v77
	v_mul_f32_e32 v48, v48, v53
	v_exp_f32_e32 v49, v49
	v_fma_f32 v46, v46, v57, v76
	v_mul_f32_e32 v48, v48, v52
	v_fma_f32 v46, v46, v56, v75
	v_mul_f32_e32 v48, v48, v51
	v_fma_f32 v46, v46, v54, v74
	v_mul_f32_e32 v48, v48, v50
	v_fma_f32 v46, v46, v53, v73
	v_mul_f32_e32 v67, v48, v49
	v_mul_f32_e32 v48, 0x3fb8aa3b, v109
	v_fma_f32 v46, v46, v52, v72
	v_exp_f32_e32 v48, v48
	v_fma_f32 v46, v46, v51, v71
	v_fma_f32 v46, v46, v50, v70
	v_fma_f32 v46, v46, v49, v69
	v_fma_f32 v93, v46, v48, v3
	v_mul_f32_e32 v46, 0x3fb8aa3b, v111
	v_exp_f32_e32 v46, v46
	v_mul_f32_e32 v67, v67, v48
	v_mul_f32_e32 v65, 0x3fb8aa3b, v65
	v_fma_f32 v93, v93, v46, v68
	v_mul_f32_e32 v67, v67, v46
	v_mov_b32_e32 v41, v189
	s_barrier
	ds_write2st64_b32 v66, v67, v93 offset1:1
	v_exp_f32_e32 v65, v65
	v_mul_f32_e32 v67, 0x3fb8aa3b, v119
	v_exp_f32_e32 v67, v67
	s_waitcnt vmcnt(0)
	v_lshlrev_b32_e32 v41, 16, v41
	v_fma_f32 v93, 0, v65, v41
	v_fma_f32 v94, v67, v93, v38
	v_mul_f32_e32 v93, 0x3fb8aa3b, v118
	v_exp_f32_e32 v93, v93
	v_mul_f32_e32 v95, v67, v65
	v_fma_f32 v96, v93, v94, v39
	v_mul_f32_e32 v94, 0x3fb8aa3b, v117
	v_exp_f32_e32 v94, v94
	v_mul_f32_e32 v95, v93, v95
	v_mul_f32_e32 v97, v94, v95
	v_mul_f32_e32 v95, 0x3fb8aa3b, v116
	v_exp_f32_e32 v95, v95
	v_fma_f32 v96, v94, v96, v40
	v_fma_f32 v96, v95, v96, v42
	v_fma_f32 v98, v55, v96, v43
	v_mul_f32_e32 v96, 0x3fb8aa3b, v115
	v_exp_f32_e32 v96, v96
	v_mul_f32_e32 v97, v95, v97
	v_mul_f32_e32 v97, v55, v97
	v_mul_f32_e32 v99, v96, v97
	v_mul_f32_e32 v97, 0x3fb8aa3b, v114
	v_exp_f32_e32 v97, v97
	v_fma_f32 v98, v96, v98, v44
	v_fma_f32 v100, v97, v98, v45
	v_mul_f32_e32 v98, 0x3fb8aa3b, v113
	v_exp_f32_e32 v98, v98
	v_mul_f32_e32 v99, v97, v99
	v_mul_f32_e32 v101, v98, v99
	v_mul_f32_e32 v99, 0x3fb8aa3b, v112
	v_exp_f32_e32 v99, v99
	v_fma_f32 v100, v98, v100, v47
	v_mul_f32_e32 v102, v99, v101
	v_mul_f32_e32 v101, 0x3fb8aa3b, v110
	v_exp_f32_e32 v101, v101
	v_fma_f32 v100, v99, v100, v86
	v_mul_f32_e32 v103, v101, v102
	v_mul_f32_e32 v102, 0x3fb8aa3b, v106
	v_exp_f32_e32 v102, v102
	v_fma_f32 v100, v101, v100, v87
	v_mul_f32_e32 v103, v102, v103
	v_mul_f32_e32 v103, v37, v103
	v_mul_f32_e32 v104, v36, v103
	v_exp_f32_e32 v103, v35
	v_fma_f32 v100, v102, v100, v88
	v_fma_f32 v100, v37, v100, v89
	v_fma_f32 v100, v36, v100, v90
	v_fma_f32 v35, v103, v100, v91
	v_exp_f32_e32 v100, v34
	v_mul_f32_e32 v104, v103, v104
	v_fma_f32 v34, v100, v35, v92
	v_mul_f32_e32 v35, v100, v104
	ds_write2st64_b32 v66, v35, v34 offset0:2 offset1:3
	v_lshlrev_b32_e32 v34, 2, v82
	v_mov_b32_e32 v35, v2
	v_lshl_add_u64 v[34:35], s[4:5], 0, v[34:35]
	v_lshl_add_u64 v[34:35], v[34:35], 0, s[14:15]
	s_lshl_b64 s[14:15], s[28:29], 11
	v_lshl_add_u64 v[104:105], v[34:35], 0, s[14:15]
	s_waitcnt lgkmcnt(0)
	s_barrier
	v_mov_b32_e32 v66, v228
	s_and_saveexec_b64 s[14:15], vcc
	s_cbranch_execz .LBB0_866
	ds_read2st64_b32 v[104:105], v63 offset1:1
	s_waitcnt vmcnt(0) lgkmcnt(0)
	v_fmac_f32_e32 v105, v66, v104
	v_mov_b32_e32 v66, v105
	s_or_b64 exec, exec, s[14:15]
	v_cmp_lt_i32_e32 vcc, 1, v85
	s_and_saveexec_b64 s[14:15], vcc
	s_cbranch_execnz .LBB0_867

; #define p (*kparams())
; __device__ __forceinline__ void lru_s3_item(CParams& p, int item, LAS unsigned char* lds) {
;     ...
;     for (int dir = 0; dir < 2; ++dir) {
;         float h = ((const float*)(p.ws + R_CR))[(size_t)((dir * 2 + b) * NCHK + c) * W + ch];
;         for (int s = 0; s < 7; ++s) { const int q = dir ? 7 - s : s; const bool use = dir ? (q > tq) : (q < tq);
;             const float a = AG[((q * 2 + dir) * 2 + 0) * 64 + j], bq = AG[((q * 2 + dir) * 2 + 1) * 64 + j]; if (use) h = a * h + bq; }
.LBB0_763:
	s_or_b64 exec, exec, s[14:15]
	s_add_i32 s14, s39, s36
	s_addk_i32 s14, 0x82
	s_ashr_i32 s15, s14, 31
	s_lshl_b64 s[14:15], s[14:15], 11
	v_lshl_add_u64 v[34:35], v[34:35], 0, s[14:15]
	v_mov_b32_e32 v34, v229
	v_cmp_gt_i32_e32 vcc, 7, v85
	s_and_saveexec_b64 s[14:15], vcc
	s_cbranch_execz .LBB0_872
	ds_read2st64_b32 v[104:105], v63 offset0:30 offset1:31
	s_waitcnt vmcnt(0) lgkmcnt(0)
	v_fmac_f32_e32 v105, v34, v104
	v_mov_b32_e32 v34, v105
	s_or_b64 exec, exec, s[14:15]
	v_cmp_gt_i32_e32 vcc, 6, v85
	s_and_saveexec_b64 s[14:15], vcc
	s_cbranch_execnz .LBB0_873
